# MODE_UP epilogue: store addresses stepped by a scalar 64-bit add instead of per-group row*ld multiplies
# baseline (speedup 1.0000x reference)
; __device__ __forceinline__ float sigm(float v) { return __builtin_amdgcn_rcpf(1.0f + __builtin_amdgcn_exp2f(-1.44269504089f * v)); }
; __device__ __forceinline__ u32x4 pack8(const f32x4& v0, const f32x4& v1) { u32x4 w; w.x = cvt_pk_bf16(v0[0], v0[1]); w.y = cvt_pk_bf16(v0[2], v0[3]); w.z = cvt_pk_bf16(v1[0], v1[1]); w.w = cvt_pk_bf16(v1[2], v1[3]); return w; }
; __device__ __forceinline__ float sumsq8(const f32x4& v0, const f32x4& v1) { return (v0[0] * v0[0] + v0[1] * v0[1]) + (v0[2] * v0[2] + v0[3] * v0[3]) + (v1[0] * v1[0] + v1[1] * v1[1]) + (v1[2] * v1[2] + v1[3] * v1[3]); }
; template <int ACT> __device__ __forceinline__ void epi_act_store(f32x4 (&acc)[2][2][4][2], const float (&rs)[2][4], bf16_t* out, int ld, int row0, int col0, float* ssqv_slot, bool want_ssq, int fq) {
;     ...
;         for (int m = 0; m < 4; ++m) { const int row = row0 + ai * 128 + m * 16; float sq = 0.f;
; #pragma unroll
;             for (int bj = 0; bj < 2; ++bj) { f32x4 v0 = acc[ai][bj][m][0] * rs[ai][m], v1 = acc[ai][bj][m][1] * rs[ai][m];
;                 if (ACT == 1) { f32x2 a = gelu_pk((f32x2){v0[0], v0[1]}), b = gelu_pk((f32x2){v0[2], v0[3]}), c = gelu_pk((f32x2){v1[0], v1[1]}), d = gelu_pk((f32x2){v1[2], v1[3]});
;                     v0 = (f32x4){a.x, a.y, b.x, b.y}; v1 = (f32x4){c.x, c.y, d.x, d.y}; sq += sumsq8(v0, v1); }
;                 if (ACT == 2) {
; #pragma unroll
;                     for (int e = 0; e < 4; ++e) { v0[e] = sigm(v0[e]); v1[e] = sigm(v1[e]); } }
;                 *(u32x4*)(out + (size_t)row * ld + col0 + bj * 128) = pack8(v0, v1); }
; __device__ __forceinline__ void epi_run(const Epi& E, f32x4 (&acc)[2][2][4][2], const Unit& u, int wr, int wc, int fr, int fq) {
;     ...
;         if (mode == MODE_UP) { epi_act_store<0>(acc, rs, E.out16, E.ld16, row0, col0, nullptr, false, fq); return; }
.LBB0_349:
	s_andn2_b64 vcc, exec, s[8:9]
	s_cbranch_vccnz .LBB0_351
	v_ashrrev_i32_e32 v213, 31, v212
	s_waitcnt lgkmcnt(0)
	v_mul_lo_u32 v131, s87, v210
	v_mul_lo_u32 v133, s86, v211
	v_mad_u64_u32 v[146:147], s[8:9], s86, v210, 0
	v_lshl_add_u64 v[144:145], v[212:213], 1, s[70:71]
	v_add3_u32 v147, v147, v133, v131
	s_lshl_b32 s8, s86, 5
	s_mov_b32 s9, 0
	s_mul_i32 s44, s86, 0xa0
	s_mov_b32 s45, 0
	v_pk_mul_f32 v[128:129], v[128:129], v[130:131] op_sel_hi:[1,0]
	v_pk_mul_f32 v[126:127], v[126:127], v[130:131] op_sel_hi:[1,0]
	v_pk_mul_f32 v[148:149], v[124:125], v[130:131] op_sel_hi:[1,0]
	v_pk_mul_f32 v[124:125], v[122:123], v[130:131] op_sel_hi:[1,0]
	v_lshl_add_u64 v[146:147], v[146:147], 1, v[144:145]
	v_cvt_pk_bf16_f32 v122, v126, v127
	v_cvt_pk_bf16_f32 v123, v128, v129
	v_cvt_pk_bf16_f32 v124, v124, v125
	v_cvt_pk_bf16_f32 v125, v148, v149
	global_store_dwordx4 v[146:147], v[122:125], off
	v_pk_mul_f32 v[120:121], v[120:121], v[130:131] op_sel_hi:[1,0]
	v_pk_mul_f32 v[118:119], v[118:119], v[130:131] op_sel_hi:[1,0]
	v_pk_mul_f32 v[122:123], v[116:117], v[130:131] op_sel_hi:[1,0]
	v_pk_mul_f32 v[116:117], v[114:115], v[130:131] op_sel_hi:[1,0]
	v_cvt_pk_bf16_f32 v114, v118, v119
	v_cvt_pk_bf16_f32 v115, v120, v121
	v_cvt_pk_bf16_f32 v116, v116, v117
	v_cvt_pk_bf16_f32 v117, v122, v123
	global_store_dwordx4 v[146:147], v[114:117], off offset:256
	s_nop 0
	v_pk_mul_f32 v[112:113], v[112:113], v[0:1] op_sel_hi:[1,0]
	v_pk_mul_f32 v[110:111], v[110:111], v[0:1] op_sel_hi:[1,0]
	v_pk_mul_f32 v[116:117], v[108:109], v[0:1] op_sel_hi:[1,0]
	v_pk_mul_f32 v[108:109], v[106:107], v[0:1] op_sel_hi:[1,0]
	v_lshl_add_u64 v[114:115], v[146:147], 0, s[8:9]
	v_cvt_pk_bf16_f32 v106, v110, v111
	v_cvt_pk_bf16_f32 v107, v112, v113
	v_cvt_pk_bf16_f32 v108, v108, v109
	v_cvt_pk_bf16_f32 v109, v116, v117
	global_store_dwordx4 v[114:115], v[106:109], off
	v_pk_mul_f32 v[104:105], v[104:105], v[0:1] op_sel_hi:[1,0]
	v_pk_mul_f32 v[102:103], v[102:103], v[0:1] op_sel_hi:[1,0]
	v_pk_mul_f32 v[106:107], v[96:97], v[0:1] op_sel_hi:[1,0]
	v_pk_mul_f32 v[96:97], v[94:95], v[0:1] op_sel_hi:[1,0]
	v_cvt_pk_bf16_f32 v94, v102, v103
	v_cvt_pk_bf16_f32 v95, v104, v105
	v_cvt_pk_bf16_f32 v96, v96, v97
	v_cvt_pk_bf16_f32 v97, v106, v107
	global_store_dwordx4 v[114:115], v[94:97], off offset:256
	v_pk_mul_f32 v[98:99], v[98:99], v[132:133] op_sel_hi:[1,0]
	v_pk_mul_f32 v[88:89], v[88:89], v[132:133] op_sel_hi:[1,0]
	v_pk_mul_f32 v[96:97], v[100:101], v[132:133] op_sel_hi:[1,0]
	v_pk_mul_f32 v[100:101], v[92:93], v[132:133] op_sel_hi:[1,0]
	v_pk_mul_f32 v[92:93], v[90:91], v[132:133] op_sel_hi:[1,0]
	v_lshl_add_u64 v[94:95], v[114:115], 0, s[8:9]
	v_cvt_pk_bf16_f32 v90, v98, v99
	v_cvt_pk_bf16_f32 v91, v96, v97
	v_cvt_pk_bf16_f32 v92, v92, v93
	v_cvt_pk_bf16_f32 v93, v100, v101
	global_store_dwordx4 v[94:95], v[90:93], off
	v_pk_mul_f32 v[86:87], v[86:87], v[132:133] op_sel_hi:[1,0]
	s_nop 0
	v_pk_mul_f32 v[90:91], v[80:81], v[132:133] op_sel_hi:[1,0]
	v_pk_mul_f32 v[80:81], v[78:79], v[132:133] op_sel_hi:[1,0]
	v_cvt_pk_bf16_f32 v78, v86, v87
	v_cvt_pk_bf16_f32 v79, v88, v89
	v_cvt_pk_bf16_f32 v80, v80, v81
	v_cvt_pk_bf16_f32 v81, v90, v91
	global_store_dwordx4 v[94:95], v[78:81], off offset:256
	v_pk_mul_f32 v[82:83], v[82:83], v[142:143] op_sel_hi:[1,0]
	v_pk_mul_f32 v[72:73], v[72:73], v[142:143] op_sel_hi:[1,0]
	v_pk_mul_f32 v[80:81], v[84:85], v[142:143] op_sel_hi:[1,0]
	v_pk_mul_f32 v[84:85], v[76:77], v[142:143] op_sel_hi:[1,0]
	v_pk_mul_f32 v[76:77], v[74:75], v[142:143] op_sel_hi:[1,0]
	v_lshl_add_u64 v[78:79], v[94:95], 0, s[8:9]
	v_cvt_pk_bf16_f32 v74, v82, v83
	v_cvt_pk_bf16_f32 v75, v80, v81
	v_cvt_pk_bf16_f32 v76, v76, v77
	v_cvt_pk_bf16_f32 v77, v84, v85
	global_store_dwordx4 v[78:79], v[74:77], off
	v_pk_mul_f32 v[70:71], v[70:71], v[142:143] op_sel_hi:[1,0]
	s_nop 0
	v_pk_mul_f32 v[74:75], v[68:69], v[142:143] op_sel_hi:[1,0]
; __device__ __forceinline__ float sigm(float v) { return __builtin_amdgcn_rcpf(1.0f + __builtin_amdgcn_exp2f(-1.44269504089f * v)); }
; __device__ __forceinline__ u32x4 pack8(const f32x4& v0, const f32x4& v1) { u32x4 w; w.x = cvt_pk_bf16(v0[0], v0[1]); w.y = cvt_pk_bf16(v0[2], v0[3]); w.z = cvt_pk_bf16(v1[0], v1[1]); w.w = cvt_pk_bf16(v1[2], v1[3]); return w; }
; __device__ __forceinline__ float sumsq8(const f32x4& v0, const f32x4& v1) { return (v0[0] * v0[0] + v0[1] * v0[1]) + (v0[2] * v0[2] + v0[3] * v0[3]) + (v1[0] * v1[0] + v1[1] * v1[1]) + (v1[2] * v1[2] + v1[3] * v1[3]); }
; template <int ACT> __device__ __forceinline__ void epi_act_store(f32x4 (&acc)[2][2][4][2], const float (&rs)[2][4], bf16_t* out, int ld, int row0, int col0, float* ssqv_slot, bool want_ssq, int fq) {
;     ...
;         for (int m = 0; m < 4; ++m) { const int row = row0 + ai * 128 + m * 16; float sq = 0.f;
; #pragma unroll
;             for (int bj = 0; bj < 2; ++bj) { f32x4 v0 = acc[ai][bj][m][0] * rs[ai][m], v1 = acc[ai][bj][m][1] * rs[ai][m];
;                 if (ACT == 1) { f32x2 a = gelu_pk((f32x2){v0[0], v0[1]}), b = gelu_pk((f32x2){v0[2], v0[3]}), c = gelu_pk((f32x2){v1[0], v1[1]}), d = gelu_pk((f32x2){v1[2], v1[3]});
;                     v0 = (f32x4){a.x, a.y, b.x, b.y}; v1 = (f32x4){c.x, c.y, d.x, d.y}; sq += sumsq8(v0, v1); }
;                 if (ACT == 2) {
; #pragma unroll
;                     for (int e = 0; e < 4; ++e) { v0[e] = sigm(v0[e]); v1[e] = sigm(v1[e]); } }
;                 *(u32x4*)(out + (size_t)row * ld + col0 + bj * 128) = pack8(v0, v1); }
; __device__ __forceinline__ void epi_run(const Epi& E, f32x4 (&acc)[2][2][4][2], const Unit& u, int wr, int wc, int fr, int fq) {
;     ...
;         if (mode == MODE_UP) { epi_act_store<0>(acc, rs, E.out16, E.ld16, row0, col0, nullptr, false, fq); return; }
	v_pk_mul_f32 v[68:69], v[66:67], v[142:143] op_sel_hi:[1,0]
	v_cvt_pk_bf16_f32 v66, v70, v71
	v_cvt_pk_bf16_f32 v67, v72, v73
	v_cvt_pk_bf16_f32 v68, v68, v69
	v_cvt_pk_bf16_f32 v69, v74, v75
	global_store_dwordx4 v[78:79], v[66:69], off offset:256
	v_pk_mul_f32 v[64:65], v[64:65], v[140:141] op_sel_hi:[1,0]
	v_pk_mul_f32 v[62:63], v[62:63], v[140:141] op_sel_hi:[1,0]
	v_pk_mul_f32 v[68:69], v[60:61], v[140:141] op_sel_hi:[1,0]
	v_pk_mul_f32 v[60:61], v[58:59], v[140:141] op_sel_hi:[1,0]
	v_lshl_add_u64 v[66:67], v[78:79], 0, s[44:45]
	v_cvt_pk_bf16_f32 v58, v62, v63
	v_cvt_pk_bf16_f32 v59, v64, v65
	v_cvt_pk_bf16_f32 v60, v60, v61
	v_cvt_pk_bf16_f32 v61, v68, v69
	global_store_dwordx4 v[66:67], v[58:61], off
	v_pk_mul_f32 v[56:57], v[56:57], v[140:141] op_sel_hi:[1,0]
	v_pk_mul_f32 v[54:55], v[54:55], v[140:141] op_sel_hi:[1,0]
	v_pk_mul_f32 v[58:59], v[52:53], v[140:141] op_sel_hi:[1,0]
	v_pk_mul_f32 v[52:53], v[50:51], v[140:141] op_sel_hi:[1,0]
	v_cvt_pk_bf16_f32 v50, v54, v55
	v_cvt_pk_bf16_f32 v51, v56, v57
	v_cvt_pk_bf16_f32 v52, v52, v53
	v_cvt_pk_bf16_f32 v53, v58, v59
	global_store_dwordx4 v[66:67], v[50:53], off offset:256
	v_pk_mul_f32 v[48:49], v[48:49], v[138:139] op_sel_hi:[1,0]
	v_pk_mul_f32 v[46:47], v[46:47], v[138:139] op_sel_hi:[1,0]
	v_pk_mul_f32 v[52:53], v[44:45], v[138:139] op_sel_hi:[1,0]
	v_pk_mul_f32 v[44:45], v[42:43], v[138:139] op_sel_hi:[1,0]
	v_lshl_add_u64 v[50:51], v[66:67], 0, s[8:9]
	v_cvt_pk_bf16_f32 v42, v46, v47
	v_cvt_pk_bf16_f32 v43, v48, v49
	v_cvt_pk_bf16_f32 v44, v44, v45
	v_cvt_pk_bf16_f32 v45, v52, v53
	global_store_dwordx4 v[50:51], v[42:45], off
	v_pk_mul_f32 v[40:41], v[40:41], v[138:139] op_sel_hi:[1,0]
	v_pk_mul_f32 v[38:39], v[38:39], v[138:139] op_sel_hi:[1,0]
	v_pk_mul_f32 v[42:43], v[36:37], v[138:139] op_sel_hi:[1,0]
	v_pk_mul_f32 v[36:37], v[34:35], v[138:139] op_sel_hi:[1,0]
	v_cvt_pk_bf16_f32 v34, v38, v39
	v_cvt_pk_bf16_f32 v35, v40, v41
	v_cvt_pk_bf16_f32 v36, v36, v37
	v_cvt_pk_bf16_f32 v37, v42, v43
	global_store_dwordx4 v[50:51], v[34:37], off offset:256
	v_pk_mul_f32 v[32:33], v[32:33], v[134:135] op_sel_hi:[1,0]
	v_pk_mul_f32 v[30:31], v[30:31], v[134:135] op_sel_hi:[1,0]
	v_pk_mul_f32 v[36:37], v[28:29], v[134:135] op_sel_hi:[1,0]
	v_pk_mul_f32 v[28:29], v[26:27], v[134:135] op_sel_hi:[1,0]
	v_lshl_add_u64 v[34:35], v[50:51], 0, s[8:9]
	v_cvt_pk_bf16_f32 v26, v30, v31
	v_cvt_pk_bf16_f32 v27, v32, v33
	v_cvt_pk_bf16_f32 v28, v28, v29
	v_cvt_pk_bf16_f32 v29, v36, v37
	global_store_dwordx4 v[34:35], v[26:29], off
	v_pk_mul_f32 v[24:25], v[24:25], v[134:135] op_sel_hi:[1,0]
	v_pk_mul_f32 v[22:23], v[22:23], v[134:135] op_sel_hi:[1,0]
	v_pk_mul_f32 v[26:27], v[20:21], v[134:135] op_sel_hi:[1,0]
	v_pk_mul_f32 v[20:21], v[18:19], v[134:135] op_sel_hi:[1,0]
	v_cvt_pk_bf16_f32 v18, v22, v23
	v_cvt_pk_bf16_f32 v19, v24, v25
	v_cvt_pk_bf16_f32 v20, v20, v21
	v_cvt_pk_bf16_f32 v21, v26, v27
	global_store_dwordx4 v[34:35], v[18:21], off offset:256
	v_pk_mul_f32 v[16:17], v[16:17], v[136:137] op_sel_hi:[1,0]
	v_pk_mul_f32 v[14:15], v[14:15], v[136:137] op_sel_hi:[1,0]
	v_pk_mul_f32 v[20:21], v[12:13], v[136:137] op_sel_hi:[1,0]
	v_pk_mul_f32 v[12:13], v[10:11], v[136:137] op_sel_hi:[1,0]
	v_lshl_add_u64 v[18:19], v[34:35], 0, s[8:9]
	v_cvt_pk_bf16_f32 v10, v14, v15
	v_cvt_pk_bf16_f32 v11, v16, v17
	v_cvt_pk_bf16_f32 v12, v12, v13
	v_cvt_pk_bf16_f32 v13, v20, v21
	global_store_dwordx4 v[18:19], v[10:13], off
	v_pk_mul_f32 v[8:9], v[8:9], v[136:137] op_sel_hi:[1,0]
	v_pk_mul_f32 v[6:7], v[6:7], v[136:137] op_sel_hi:[1,0]
	v_pk_mul_f32 v[10:11], v[4:5], v[136:137] op_sel_hi:[1,0]
	v_pk_mul_f32 v[4:5], v[2:3], v[136:137] op_sel_hi:[1,0]
	v_cvt_pk_bf16_f32 v2, v6, v7
	v_cvt_pk_bf16_f32 v3, v8, v9
	v_cvt_pk_bf16_f32 v4, v4, v5
	v_cvt_pk_bf16_f32 v5, v10, v11
	global_store_dwordx4 v[18:19], v[2:5], off offset:256
